# x15 + attention unit prologue: the 3 serialized Q-tail loads and the first K/V tile loads issued together (one wait instead of five)
# baseline (speedup 1.0000x reference)
; #define LAS __attribute__((address_space(3)))
; __device__ __forceinline__ int v_st(int k, int c) { const int kk = (k & ~0xC) | ((k & 4) << 1) | ((k & 8) >> 1); return ((kk >> 3) * 4 + (c >> 5)) * 512 + ((kk & 7) * 32 + (c & 31)) * 2; }
; #define SLOAD(kt) do { SLOADV(kt); SLOADK(kt); } while (0)
; #define SWAIT() asm volatile("s_waitcnt vmcnt(0)" ::: "memory")
; __device__ __forceinline__ void qkt(f32x16& p0, f32x16& p1, const LAS unsigned char* Ks, const bf16x8* qr, const LAS unsigned char* qrp, int qsw, const int (&kq)[4], int hi) {
;     p0 = f32x16{}; p1 = f32x16{};
; #pragma unroll
;     for (int d0 = 0; d0 < 12; ++d0) {
;         const bf16x8 b0 = *(const LAS bf16x8*)(Ks + kq[d0 & 3] + 128 * (d0 >> 2));
;         const bf16x8 b1 = *(const LAS bf16x8*)(Ks + kq[d0 & 3] + 128 * (d0 >> 2) + 32 * 384);
;         bf16x8 qv; if (d0 < 8) qv = qr[d0]; else qv = *(const LAS bf16x8*)(qrp + (((2 * (d0 - 8) + hi) ^ qsw) << 4));
;         p0 = __builtin_amdgcn_mfma_f32_32x32x16_bf16(b0, qv, p0, 0, 0, 0);
;         p1 = __builtin_amdgcn_mfma_f32_32x32x16_bf16(b1, qv, p1, 0, 0, 0); }
; }
; template <bool DIRECT> ...
;     ...
;     const bf16_t* Qw = QKV + (size_t)(qrow0 + wid * QBLK + r32) * NUP + h * 192 + hi * 8;
; #pragma unroll
;     for (int d0 = 0; d0 < 8; ++d0) qr[d0] = *(const bf16x8*)(Qw + d0 * 16);
;     LAS unsigned char* qrp = lds + OFF_QR + wid * 4096 + r32 * 128; const int qsw = (r32 >> 1) & 7;
;     int kq[4];
; #pragma unroll
;     for (int q = 0; q < 4; ++q) kq[q] = 384 * r32 + (((2 * q + hi) ^ qsw) << 4);
; #pragma unroll
;     for (int d0 = 8; d0 < 12; ++d0) *(LAS bf16x8*)(qrp + (((2 * (d0 - 8) + hi) ^ qsw) << 4)) = *(const bf16x8*)(Qw + d0 * 16);
;     const int sr = tid >> 4, sc = (tid & 15) * 8;
;     const int vst0 = v_st(sr, sc);
;     const int kst0 = KSWZ(sr, sc * 2);
;     const int krst = KSWZ(tid >> 3, 256 + (tid & 7) * 16);
;     const unsigned voffV = (unsigned)(sr * NUP + sc) * 2u, voffR = (unsigned)((tid >> 3) * INWP + (tid & 7) * 8) * 2u;
;     const char* Vb = (const char*)(QKV + 768 + h * 256 + 128); const char* Kb = (const char*)(QKV + 768 + h * 256); const char* Rb = (const char*)(Z + ZKR);
;     const int vb0 = (int)(uintptr_t)V_lds + v_rd_base(lane);
;     bf16x8 vs0, vs1, ks0, ks1, ks2;
;     ...
;     f32x16 pA0, pA1, pB0, pB1; float mnA, mnB, alA, alB; bf16x8 pa0, pa1, pa2, pa3;
;     SLOAD(0); SWAIT(); SWRITE(0); __syncthreads();
.LBB0_835:
	s_bfe_u32 s19, s55, 0x10002
	s_bfe_u32 s56, s55, 0x10003
	s_lshl_b32 s18, s19, 12
	s_lshl_b32 s19, s19, 8
	s_bitset1_b32 s19, 13
	s_mul_i32 s20, s56, 0x880
	s_add_i32 s21, s20, s19
	s_or_b32 s24, s20, s18
	s_or_b32 s23, s21, 64
	s_addk_i32 s21, 0x80
	s_add_i32 s22, s24, 0xffffff80
	s_cmp_eq_u32 s56, 0
	s_cselect_b32 s22, s21, s22
	s_addk_i32 s24, 0xff40
	s_cmp_eq_u32 s56, 0
	s_cselect_b32 s23, s23, s24
	s_add_i32 s21, s18, 0xffffff00
	s_cmp_eq_u32 s56, 0
	s_cselect_b32 s26, s19, s21
	s_lshl_b32 s24, s55, 4
	s_and_b32 s24, s24, 0xffffff00
	s_add_i32 s24, s18, s24
	v_add_u32_e32 v196, s24, v178
	s_and_b32 s57, s55, 3
	v_or_b32_e32 v162, v196, v154
	v_mov_b64_e32 v[0:1], s[44:45]
	v_mad_i64_i32 v[0:1], s[24:25], v162, s13, v[0:1]
	s_mul_i32 s76, s57, 0x180
	v_lshl_add_u64 v[0:1], v[0:1], 0, s[76:77]
	v_mov_b32_e32 v161, v97
	v_lshl_add_u64 v[4:5], v[0:1], 0, v[160:161]
	global_load_dwordx4 v[126:129], v[4:5], off
	global_load_dwordx4 v[122:125], v[4:5], off offset:32
	global_load_dwordx4 v[118:121], v[4:5], off offset:64
	global_load_dwordx4 v[114:117], v[4:5], off offset:96
	global_load_dwordx4 v[110:113], v[4:5], off offset:128
	global_load_dwordx4 v[106:109], v[4:5], off offset:160
	global_load_dwordx4 v[102:105], v[4:5], off offset:192
	global_load_dwordx4 v[98:101], v[4:5], off offset:224
	global_load_dwordx4 v[0:3], v[4:5], off offset:256
	global_load_dwordx4 v[20:23], v[4:5], off offset:288
	global_load_dwordx4 v[24:27], v[4:5], off offset:320
	global_load_dwordx4 v[28:31], v[4:5], off offset:352
	v_add_u32_e32 v207, v187, v179
	v_add_u32_e32 v206, v187, v181
	v_add_u32_e32 v197, v187, v183
	s_lshl_b32 s24, s57, 9
	s_add_u32 s40, s53, s24
	s_addc_u32 s41, s54, 0
	s_add_i32 s26, s26, s20
	s_mul_i32 s24, s26, 0xe00
	s_mul_hi_i32 s25, s26, 0xe00
	s_add_u32 s24, s40, s24
	s_addc_u32 s25, s41, s25
	v_lshl_add_u64 v[8:9], s[24:25], 0, v[156:157]
	s_mov_b32 s27, 0x1c000
	v_add_u32_e32 v161, v187, v185
	v_add_co_u32_e32 v12, vcc, s27, v8
	v_mad_i64_i32 v[16:17], s[24:25], s26, v218, v[158:159]
	s_nop 0
	v_addc_co_u32_e32 v13, vcc, 0, v9, vcc
	v_add_u32_e32 v209, 0, v180
	v_add_u32_e32 v211, 0, v182
	v_add_u32_e32 v210, 0, v184
	v_add_u32_e32 v208, 0, v186
	s_mul_i32 s24, s23, 0xe00
	s_mul_hi_i32 s25, s23, 0xe00
	s_mov_b32 s76, s77
	s_mov_b32 s78, s77
	s_mov_b32 s79, s77
	s_mov_b32 s80, s77
	s_mov_b32 s81, s77
	s_mov_b32 s82, s77
	s_mov_b32 s83, s77
	s_mov_b32 s84, s77
	s_mov_b32 s85, s77
	s_mov_b32 s86, s77
	s_mov_b32 s87, s77
	s_mov_b32 s88, s77
	s_mov_b32 s89, s77
	s_mov_b32 s90, s77
	s_mov_b32 s91, s77
	v_ashrrev_i32_e32 v163, 31, v162
	s_mov_b32 s58, 1
	v_lshl_add_u64 v[164:165], s[40:41], 0, v[156:157]
	v_mov_b32_e32 v212, 0
	global_load_dwordx4 v[32:35], v[8:9], off offset:256
	global_load_dwordx4 v[4:7], v[12:13], off offset:256
	s_nop 0
	global_load_dwordx4 v[8:11], v[8:9], off
	s_nop 0
	global_load_dwordx4 v[12:15], v[12:13], off
	s_nop 0
	global_load_dwordx4 v[16:19], v[16:17], off
	s_waitcnt vmcnt(5)
	ds_write_b128 v207, v[0:3]
	ds_write_b128 v206, v[20:23]
	ds_write_b128 v197, v[24:27]
	ds_write_b128 v161, v[28:31]
	s_waitcnt vmcnt(4)
	ds_write_b128 v191, v[32:35]
	s_waitcnt vmcnt(3)
	ds_write_b128 v191, v[4:7] offset:8192
	v_add_u32_e32 v0, 0, v188
	s_waitcnt vmcnt(2)
	ds_write_b128 v0, v[8:11] offset:49152
	s_waitcnt vmcnt(1)
	ds_write_b128 v0, v[12:15] offset:61440
	v_add_u32_e32 v0, 0, v189
	s_waitcnt vmcnt(0)
	ds_write_b128 v0, v[16:19] offset:49152
	s_waitcnt lgkmcnt(0)
	s_barrier
	ds_read_b128 v[16:19], v209 offset:49152
	ds_read_b128 v[20:23], v209 offset:61440
	s_waitcnt lgkmcnt(1)
	v_mfma_f32_32x32x16_bf16 v[32:47], v[16:19], v[126:129], 0
	ds_read_b128 v[48:51], v211 offset:49152
	ds_read_b128 v[52:55], v211 offset:61440
	v_mov_b64_e32 v[0:1], s[76:77]
	v_mov_b64_e32 v[14:15], s[90:91]
	v_mov_b64_e32 v[2:3], s[78:79]
	v_mov_b64_e32 v[4:5], s[80:81]
	v_mov_b64_e32 v[6:7], s[82:83]
	v_mov_b64_e32 v[8:9], s[84:85]
	s_waitcnt lgkmcnt(2)
	v_mfma_f32_32x32x16_bf16 v[16:31], v[20:23], v[126:129], 0
	v_mov_b64_e32 v[10:11], s[86:87]
	v_mov_b64_e32 v[12:13], s[88:89]
	s_waitcnt lgkmcnt(1)
	v_mfma_f32_32x32x16_bf16 v[32:47], v[48:51], v[122:125], v[32:47]
	s_waitcnt lgkmcnt(0)
	v_mfma_f32_32x32x16_bf16 v[16:31], v[52:55], v[122:125], v[16:31]
	ds_read_b128 v[48:51], v210 offset:49152
	ds_read_b128 v[52:55], v210 offset:61440
	s_waitcnt lgkmcnt(1)
	v_mfma_f32_32x32x16_bf16 v[32:47], v[48:51], v[118:121], v[32:47]
	s_waitcnt lgkmcnt(0)
	v_mfma_f32_32x32x16_bf16 v[16:31], v[52:55], v[118:121], v[16:31]
	ds_read_b128 v[48:51], v208 offset:49152
	ds_read_b128 v[52:55], v208 offset:61440
	s_waitcnt lgkmcnt(1)
	v_mfma_f32_32x32x16_bf16 v[32:47], v[48:51], v[114:117], v[32:47]
	s_waitcnt lgkmcnt(0)
	v_mfma_f32_32x32x16_bf16 v[16:31], v[52:55], v[114:117], v[16:31]
	ds_read_b128 v[48:51], v209 offset:49280
	ds_read_b128 v[52:55], v209 offset:61568
	s_waitcnt lgkmcnt(1)
	v_mfma_f32_32x32x16_bf16 v[32:47], v[48:51], v[110:113], v[32:47]
	s_waitcnt lgkmcnt(0)
	v_mfma_f32_32x32x16_bf16 v[16:31], v[52:55], v[110:113], v[16:31]
	ds_read_b128 v[48:51], v211 offset:49280
	ds_read_b128 v[52:55], v211 offset:61568
	s_waitcnt lgkmcnt(1)
	v_mfma_f32_32x32x16_bf16 v[32:47], v[48:51], v[106:109], v[32:47]
	s_waitcnt lgkmcnt(0)
	v_mfma_f32_32x32x16_bf16 v[16:31], v[52:55], v[106:109], v[16:31]
	ds_read_b128 v[48:51], v210 offset:49280
	ds_read_b128 v[52:55], v210 offset:61568
	s_waitcnt lgkmcnt(1)
	v_mfma_f32_32x32x16_bf16 v[32:47], v[48:51], v[102:105], v[32:47]
	s_waitcnt lgkmcnt(0)
	v_mfma_f32_32x32x16_bf16 v[16:31], v[52:55], v[102:105], v[16:31]
	ds_read_b128 v[48:51], v208 offset:49280
	ds_read_b128 v[52:55], v208 offset:61568
	s_waitcnt lgkmcnt(1)
; #define SLOAD(kt) do { SLOADV(kt); SLOADK(kt); } while (0)
; #define SWRITE(b) do { *(LAS bf16x8*)(V_lds + (b) * SHM_V + vst0) = vs0; *(LAS bf16x8*)(V_lds + (b) * SHM_V + vst0 + 8192) = vs1; \
;     *(LAS bf16x8*)(K_lds + (b) * SHM_K + kst0) = ks0; *(LAS bf16x8*)(K_lds + (b) * SHM_K + kst0 + 32 * 384) = ks1; *(LAS bf16x8*)(K_lds + (b) * SHM_K + krst) = ks2; } while (0)
; #define SWAIT() asm volatile("s_waitcnt vmcnt(0)" ::: "memory")
; __device__ __forceinline__ void partialSM(f32x16& p0, f32x16& p1, float& m_reg, float& mn, float& alpha) {
;     constexpr float C = SCALE * 1.4426950408889634f;
;     float pmax = p0[0];
; #pragma unroll
;     for (int r = 1; r < 16; ++r) pmax = fmaxf(pmax, p0[r]);
; #pragma unroll
;     for (int r = 0; r < 16; ++r) pmax = fmaxf(pmax, p1[r]);
;     { auto rr = __builtin_amdgcn_permlane32_swap(__float_as_uint(pmax), __float_as_uint(pmax), false, false);
;       pmax = fmaxf(__uint_as_float(rr[0]), __uint_as_float(rr[1])); }
;     if (__builtin_expect(__all(pmax - m_reg <= THR / SCALE), 1)) { mn = m_reg; alpha = 1.f; }
;     else { mn = fmaxf(m_reg, pmax); alpha = __builtin_amdgcn_exp2f((m_reg - mn) * C); m_reg = mn; }
;     const float mnC = -mn * C;
; #pragma unroll
;     for (int r = 0; r < 16; ++r) p0[r] = fmaf(p0[r], C, mnC);
; #pragma unroll
;     for (int r = 0; r < 16; ++r) p1[r] = fmaf(p1[r], C, mnC);
; #pragma unroll
;     for (int r = 0; r < 16; ++r) p0[r] = __builtin_amdgcn_exp2f(p0[r]);
; }
; template <bool DIRECT> ...
;     ...
;     qkt(pA0, pA1, K_lds, qr, qrp, qsw, kq, hi); partialSM(pA0, pA1, m_reg, mnA, alA);
;     SLOAD(1);
;     SWAIT(); SWRITE(1); __syncthreads();
;     if (2 < NT) SLOAD(2);
	v_mfma_f32_32x32x16_bf16 v[32:47], v[48:51], v[98:101], v[32:47]
	s_waitcnt lgkmcnt(0)
	v_mfma_f32_32x32x16_bf16 v[16:31], v[52:55], v[98:101], v[16:31]
	ds_read_b128 v[48:51], v209 offset:49408
	ds_read_b128 v[52:55], v209 offset:61696
	ds_read_b128 v[56:59], v207
	s_waitcnt lgkmcnt(0)
	v_mfma_f32_32x32x16_bf16 v[32:47], v[48:51], v[56:59], v[32:47]
	v_mfma_f32_32x32x16_bf16 v[16:31], v[52:55], v[56:59], v[16:31]
	ds_read_b128 v[48:51], v211 offset:49408
	ds_read_b128 v[52:55], v211 offset:61696
	ds_read_b128 v[56:59], v206
	s_waitcnt lgkmcnt(0)
	v_mfma_f32_32x32x16_bf16 v[32:47], v[48:51], v[56:59], v[32:47]
	v_mfma_f32_32x32x16_bf16 v[16:31], v[52:55], v[56:59], v[16:31]
	ds_read_b128 v[48:51], v210 offset:49408
	ds_read_b128 v[52:55], v210 offset:61696
	ds_read_b128 v[56:59], v197
	s_waitcnt lgkmcnt(0)
	v_mfma_f32_32x32x16_bf16 v[32:47], v[48:51], v[56:59], v[32:47]
	v_mfma_f32_32x32x16_bf16 v[16:31], v[52:55], v[56:59], v[16:31]
	ds_read_b128 v[48:51], v208 offset:49408
	ds_read_b128 v[52:55], v208 offset:61696
	ds_read_b128 v[56:59], v161
	s_waitcnt lgkmcnt(0)
	v_mfma_f32_32x32x16_bf16 v[32:47], v[48:51], v[56:59], v[32:47]
	v_mfma_f32_32x32x16_bf16 v[16:31], v[52:55], v[56:59], v[16:31]
	s_nop 10
	v_max_f32_e32 v48, v33, v33
	v_max_f32_e32 v49, v32, v32
	v_max_f32_e32 v48, v49, v48
	v_max3_f32 v48, v48, v34, v35
	v_max3_f32 v48, v48, v36, v37
	v_max3_f32 v48, v48, v38, v39
	v_max3_f32 v48, v48, v40, v41
	v_max3_f32 v48, v48, v42, v43
	v_max3_f32 v48, v48, v44, v45
	v_max3_f32 v48, v48, v46, v47
	v_max3_f32 v48, v48, v16, v17
	v_max3_f32 v48, v48, v18, v19
	v_max3_f32 v48, v48, v20, v21
	v_max3_f32 v48, v48, v22, v23
	v_max3_f32 v48, v48, v24, v25
	v_max3_f32 v48, v48, v26, v27
	v_max3_f32 v48, v48, v28, v29
	v_max3_f32 v48, v48, v30, v31
	v_mov_b32_e32 v49, v48
	s_nop 1
	v_permlane32_swap_b32_e32 v48, v49
	v_max_f32_e32 v49, v49, v49
	v_max_f32_e32 v48, v48, v48
	v_max_f32_e32 v48, v48, v49
	v_add_f32_e32 v49, 0x7149f2ca, v48
	v_max_f32_e32 v48, 0xf149f2ca, v48
	v_cmp_ge_f32_e32 vcc, s14, v49
	v_sub_f32_e32 v49, 0xf149f2ca, v48
	v_mul_f32_e32 v49, 0x3dd53b94, v49
	s_cmp_eq_u64 vcc, exec
	v_exp_f32_e32 v49, v49
	s_cselect_b64 vcc, -1, 0
	v_cndmask_b32_e32 v221, v48, v219, vcc
	v_mul_f32_e32 v48, 0xbdd53b94, v221
	v_cndmask_b32_e64 v213, v49, 1.0, vcc
	v_mov_b32_e32 v49, v48
	s_add_u32 s24, s40, s24
	v_fmac_f32_e32 v49, 0x3dd53b94, v47
	s_addc_u32 s25, s41, s25
	v_pk_fma_f32 v[168:169], v[24:25], s[8:9], v[48:49] op_sel_hi:[1,0,0]
	v_lshl_add_u64 v[24:25], s[24:25], 0, v[156:157]
	v_pk_fma_f32 v[152:153], v[28:29], s[8:9], v[48:49] op_sel_hi:[1,0,0]
	v_add_co_u32_e32 v28, vcc, s27, v24
	v_pk_fma_f32 v[174:175], v[18:19], s[8:9], v[48:49] op_sel_hi:[1,0,0]
	v_pk_fma_f32 v[176:177], v[16:17], s[8:9], v[48:49] op_sel_hi:[1,0,0]
	global_load_dwordx4 v[16:19], v[24:25], off offset:256
	v_addc_co_u32_e32 v29, vcc, 0, v25, vcc
	v_fmamk_f32 v32, v32, 0x3dd53b94, v48
	v_fmamk_f32 v33, v33, 0x3dd53b94, v48
	v_pk_fma_f32 v[150:151], v[30:31], s[8:9], v[48:49] op_sel_hi:[1,0,0]
	v_pk_fma_f32 v[166:167], v[26:27], s[8:9], v[48:49] op_sel_hi:[1,0,0]
	v_pk_fma_f32 v[170:171], v[22:23], s[8:9], v[48:49] op_sel_hi:[1,0,0]
	v_pk_fma_f32 v[172:173], v[20:21], s[8:9], v[48:49] op_sel_hi:[1,0,0]
	global_load_dwordx4 v[20:23], v[28:29], off offset:256
	s_nop 0
	global_load_dwordx4 v[24:27], v[24:25], off
	s_nop 0
	global_load_dwordx4 v[28:31], v[28:29], off
	v_fmamk_f32 v34, v34, 0x3dd53b94, v48
	v_fmamk_f32 v35, v35, 0x3dd53b94, v48
	v_exp_f32_e32 v235, v32
	v_exp_f32_e32 v237, v33
	v_mad_i64_i32 v[32:33], s[24:25], s23, v218, v[158:159]
	v_exp_f32_e32 v233, v34
	v_exp_f32_e32 v236, v35
	global_load_dwordx4 v[32:35], v[32:33], off
	s_add_i32 s23, 0, 0x12000
	s_waitcnt vmcnt(0)
	s_waitcnt vmcnt(4)
	ds_write_b128 v191, v[16:19] offset:16384
	s_waitcnt vmcnt(3)
	ds_write_b128 v191, v[20:23] offset:24576
	v_add_u32_e32 v16, s23, v188
	s_mul_i32 s24, s22, 0xe00
	s_waitcnt vmcnt(2)
	ds_write_b128 v16, v[24:27]
	s_waitcnt vmcnt(1)
	ds_write_b128 v16, v[28:31] offset:12288
	v_add_u32_e32 v16, s23, v189
	s_mul_hi_i32 s23, s22, 0xe00
	s_add_u32 s24, s40, s24
	s_addc_u32 s25, s41, s23
	v_mad_i64_i32 v[20:21], s[22:23], s22, v218, v[158:159]
	v_fmamk_f32 v36, v36, 0x3dd53b94, v48
	s_waitcnt vmcnt(0)
	ds_write_b128 v16, v[32:35]
	v_lshl_add_u64 v[16:17], s[24:25], 0, v[156:157]
	v_add_co_u32_e32 v18, vcc, s27, v16
	s_waitcnt lgkmcnt(0)
	s_nop 0
	v_addc_co_u32_e32 v19, vcc, 0, v17, vcc
	s_barrier
	global_load_dwordx4 v[130:133], v[16:17], off offset:256
	global_load_dwordx4 v[134:137], v[18:19], off offset:256
	global_load_dwordx4 v[138:141], v[20:21], off
	global_load_dwordx4 v[146:149], v[18:19], off
	global_load_dwordx4 v[142:145], v[16:17], off
	v_fmamk_f32 v37, v37, 0x3dd53b94, v48
	v_fmamk_f32 v38, v38, 0x3dd53b94, v48
	v_fmamk_f32 v39, v39, 0x3dd53b94, v48
	v_fmamk_f32 v40, v40, 0x3dd53b94, v48
	v_fmamk_f32 v41, v41, 0x3dd53b94, v48
	v_fmamk_f32 v42, v42, 0x3dd53b94, v48
	v_fmamk_f32 v43, v43, 0x3dd53b94, v48
	v_fmamk_f32 v44, v44, 0x3dd53b94, v48
	v_fmamk_f32 v45, v45, 0x3dd53b94, v48
	v_fmamk_f32 v46, v46, 0x3dd53b94, v48
	v_exp_f32_e32 v232, v36
	v_exp_f32_e32 v234, v37
	v_exp_f32_e32 v230, v38
	v_exp_f32_e32 v231, v39
	v_exp_f32_e32 v227, v40
	v_exp_f32_e32 v229, v41
	v_exp_f32_e32 v226, v42
	v_exp_f32_e32 v228, v43
	v_exp_f32_e32 v223, v44
	v_exp_f32_e32 v225, v45
	v_exp_f32_e32 v222, v46
	v_exp_f32_e32 v224, v49
	v_mov_b64_e32 v[62:63], v[14:15]
	v_mov_b64_e32 v[46:47], v[14:15]
	v_mov_b64_e32 v[30:31], v[14:15]
	v_mov_b64_e32 v[60:61], v[12:13]
	v_mov_b64_e32 v[58:59], v[10:11]
	v_mov_b64_e32 v[56:57], v[8:9]
	v_mov_b64_e32 v[54:55], v[6:7]
	v_mov_b64_e32 v[52:53], v[4:5]
	v_mov_b64_e32 v[50:51], v[2:3]
	v_mov_b64_e32 v[48:49], v[0:1]
	v_mov_b64_e32 v[44:45], v[12:13]
	v_mov_b64_e32 v[42:43], v[10:11]
	v_mov_b64_e32 v[40:41], v[8:9]
	v_mov_b64_e32 v[38:39], v[6:7]
	v_mov_b64_e32 v[36:37], v[4:5]
	v_mov_b64_e32 v[34:35], v[2:3]
	v_mov_b64_e32 v[32:33], v[0:1]
	v_mov_b64_e32 v[28:29], v[12:13]
	v_mov_b64_e32 v[26:27], v[10:11]
	v_mov_b64_e32 v[24:25], v[8:9]
	v_mov_b64_e32 v[22:23], v[6:7]
	v_mov_b64_e32 v[20:21], v[4:5]
	v_mov_b64_e32 v[18:19], v[2:3]
	v_mov_b64_e32 v[16:17], v[0:1]
	s_mov_b32 s22, 1
